# config B + barrier leader releases before own L1 invalidate + hand-written rwkv scanner loop (16 VALU per step, deferred y reduce-scatter, cross-chunk operand prefetch)
# baseline (speedup 1.0000x reference)
.LBB0_472:
	s_mov_b32 s78, 0xcccccccc
	s_mov_b32 s79, 0xcccccccc
	s_mov_b32 s96, 0xaaaaaaaa
	s_mov_b32 s97, 0xaaaaaaaa
	s_add_i32 s77, s36, s83
	s_and_b32 s86, s77, 3
	s_mul_i32 s12, s86, 0x5400
	s_lshl_b32 s86, s86, 2
	s_add_i32 s77, s77, 1
	v_add_u32_e32 v32, s12, v183
	v_add_u32_e32 v33, s12, v184
	v_add_u32_e32 v33, 0x5000, v33
.Lsc_pollentry:
	s_add_i32 s13, s86, 0x15000
	v_mov_b32_e32 v26, s13
.Lsc_poll:
	ds_read_b32 v25, v26
	s_waitcnt lgkmcnt(0)
	v_cmp_le_u32_e32 vcc, s77, v25
	s_cbranch_vccnz .Lsc_go
	s_sleep 1
	s_branch .Lsc_poll
.Lsc_go:
	ds_read_b128 v[80:83], v32 offset:768
	ds_read_b128 v[76:79], v32 offset:512
	ds_read2_b32 v[148:149], v33 offset0:0 offset1:16
	ds_read_b128 v[68:71], v32 offset:0
	ds_read_b128 v[84:87], v32 offset:1024
	ds_read_b128 v[72:75], v32 offset:256
	ds_read_b128 v[100:103], v32 offset:2048
	ds_read_b128 v[96:99], v32 offset:1792
	ds_read_b128 v[88:91], v32 offset:1280
	ds_read_b128 v[104:107], v32 offset:2304
	ds_read_b128 v[92:95], v32 offset:1536
.Lsc_chunk:
	s_waitcnt lgkmcnt(5)
	v_pk_mul_f32 v[156:157], v[54:55], v[80:81]
	v_pk_fma_f32 v[156:157], v[56:57], v[82:83], v[156:157]
	v_add_f32_e32 v2, v156, v157
	ds_read_b128 v[120:123], v32 offset:3328
	ds_read_b128 v[116:119], v32 offset:3072
	v_add_f32_dpp v2, v2, v2 row_ror:8 row_mask:0xf bank_mask:0xf bound_ctrl:1
	ds_read2_b32 v[150:151], v33 offset0:32 offset1:48
	v_pk_mul_f32 v[4:5], v[76:77], v[148:149] op_sel_hi:[1,0]
	v_add_f32_dpp v2, v2, v2 row_ror:4 row_mask:0xf bank_mask:0xf bound_ctrl:1
	v_pk_mul_f32 v[6:7], v[78:79], v[148:149] op_sel_hi:[1,0]
	v_pk_fma_f32 v[4:5], v[54:55], v[68:69], v[4:5]
	v_add_f32_dpp v2, v2, v2 row_ror:2 row_mask:0xf bank_mask:0xf bound_ctrl:1
	v_pk_fma_f32 v[6:7], v[56:57], v[70:71], v[6:7]
	ds_read_b128 v[108:111], v32 offset:2560
	v_add_f32_dpp v2, v2, v2 row_ror:1 row_mask:0xf bank_mask:0xf bound_ctrl:1
	v_pk_fma_f32 v[54:55], v[84:85], v[2:3], v[4:5] op_sel_hi:[1,0,1] neg_lo:[1,0,0] neg_hi:[1,0,0]
	v_pk_fma_f32 v[56:57], v[86:87], v[2:3], v[6:7] op_sel_hi:[1,0,1] neg_lo:[1,0,0] neg_hi:[1,0,0]
	ds_read_b128 v[124:127], v32 offset:3584
	ds_read_b128 v[112:115], v32 offset:2816
	s_waitcnt lgkmcnt(6)
	v_pk_mul_f32 v[156:157], v[54:55], v[100:101]
	v_pk_fma_f32 v[156:157], v[56:57], v[102:103], v[156:157]
	v_add_f32_e32 v2, v156, v157
	v_pk_mul_f32 v[8:9], v[54:55], v[72:73]
	v_pk_fma_f32 v[8:9], v[56:57], v[74:75], v[8:9]
	v_add_f32_dpp v2, v2, v2 row_ror:8 row_mask:0xf bank_mask:0xf bound_ctrl:1
	v_add_f32_e32 v66, v8, v9
	v_pk_mul_f32 v[4:5], v[96:97], v[148:149] op_sel:[0,1] op_sel_hi:[1,1]
	v_add_f32_dpp v2, v2, v2 row_ror:4 row_mask:0xf bank_mask:0xf bound_ctrl:1
	v_pk_mul_f32 v[6:7], v[98:99], v[148:149] op_sel:[0,1] op_sel_hi:[1,1]
	v_pk_fma_f32 v[4:5], v[54:55], v[88:89], v[4:5]
	v_add_f32_dpp v2, v2, v2 row_ror:2 row_mask:0xf bank_mask:0xf bound_ctrl:1
	v_pk_fma_f32 v[6:7], v[56:57], v[90:91], v[6:7]
	ds_read_b128 v[140:143], v32 offset:4608
	v_add_f32_dpp v2, v2, v2 row_ror:1 row_mask:0xf bank_mask:0xf bound_ctrl:1
	v_pk_fma_f32 v[54:55], v[104:105], v[2:3], v[4:5] op_sel_hi:[1,0,1] neg_lo:[1,0,0] neg_hi:[1,0,0]
	v_pk_fma_f32 v[56:57], v[106:107], v[2:3], v[6:7] op_sel_hi:[1,0,1] neg_lo:[1,0,0] neg_hi:[1,0,0]
	ds_read_b128 v[136:139], v32 offset:4352
	ds_read_b128 v[128:131], v32 offset:3840
	ds_read_b128 v[144:147], v32 offset:4864
	ds_read_b128 v[132:135], v32 offset:4096
	s_waitcnt lgkmcnt(5)
	v_pk_mul_f32 v[156:157], v[54:55], v[120:121]
	v_pk_fma_f32 v[156:157], v[56:57], v[122:123], v[156:157]
	v_add_f32_e32 v2, v156, v157
	v_pk_mul_f32 v[8:9], v[54:55], v[92:93]
	v_pk_fma_f32 v[8:9], v[56:57], v[94:95], v[8:9]
	v_add_f32_dpp v2, v2, v2 row_ror:8 row_mask:0xf bank_mask:0xf bound_ctrl:1
	v_add_f32_e32 v10, v8, v9
	v_pk_mul_f32 v[4:5], v[116:117], v[150:151] op_sel_hi:[1,0]
	v_add_f32_dpp v2, v2, v2 row_ror:4 row_mask:0xf bank_mask:0xf bound_ctrl:1
	v_pk_mul_f32 v[6:7], v[118:119], v[150:151] op_sel_hi:[1,0]
	v_pk_fma_f32 v[4:5], v[54:55], v[108:109], v[4:5]
	v_add_f32_dpp v2, v2, v2 row_ror:2 row_mask:0xf bank_mask:0xf bound_ctrl:1
	v_pk_fma_f32 v[6:7], v[56:57], v[110:111], v[6:7]
	ds_read_b128 v[80:83], v32 offset:5888
	v_add_f32_dpp v2, v2, v2 row_ror:1 row_mask:0xf bank_mask:0xf bound_ctrl:1
	v_pk_fma_f32 v[54:55], v[124:125], v[2:3], v[4:5] op_sel_hi:[1,0,1] neg_lo:[1,0,0] neg_hi:[1,0,0]
	v_pk_fma_f32 v[56:57], v[126:127], v[2:3], v[6:7] op_sel_hi:[1,0,1] neg_lo:[1,0,0] neg_hi:[1,0,0]
	ds_read_b128 v[76:79], v32 offset:5632
	ds_read2_b32 v[152:153], v33 offset0:64 offset1:80
	ds_read_b128 v[68:71], v32 offset:5120
	ds_read_b128 v[84:87], v32 offset:6144
	ds_read_b128 v[72:75], v32 offset:5376
	s_waitcnt lgkmcnt(6)
	v_pk_mul_f32 v[156:157], v[54:55], v[140:141]
	v_pk_fma_f32 v[156:157], v[56:57], v[142:143], v[156:157]
	v_add_f32_e32 v2, v156, v157
	v_pk_mul_f32 v[8:9], v[54:55], v[112:113]
	v_pk_fma_f32 v[8:9], v[56:57], v[114:115], v[8:9]
	v_add_f32_dpp v2, v2, v2 row_ror:8 row_mask:0xf bank_mask:0xf bound_ctrl:1
	v_add_f32_e32 v11, v8, v9
	v_pk_mul_f32 v[4:5], v[136:137], v[150:151] op_sel:[0,1] op_sel_hi:[1,1]
	v_add_f32_dpp v2, v2, v2 row_ror:4 row_mask:0xf bank_mask:0xf bound_ctrl:1
	v_pk_mul_f32 v[6:7], v[138:139], v[150:151] op_sel:[0,1] op_sel_hi:[1,1]
	v_pk_fma_f32 v[4:5], v[54:55], v[128:129], v[4:5]
	v_add_f32_dpp v2, v2, v2 row_ror:2 row_mask:0xf bank_mask:0xf bound_ctrl:1
	v_pk_fma_f32 v[6:7], v[56:57], v[130:131], v[6:7]
	ds_read_b128 v[100:103], v32 offset:7168
	v_add_f32_dpp v2, v2, v2 row_ror:1 row_mask:0xf bank_mask:0xf bound_ctrl:1
	v_pk_fma_f32 v[54:55], v[144:145], v[2:3], v[4:5] op_sel_hi:[1,0,1] neg_lo:[1,0,0] neg_hi:[1,0,0]
	v_pk_fma_f32 v[56:57], v[146:147], v[2:3], v[6:7] op_sel_hi:[1,0,1] neg_lo:[1,0,0] neg_hi:[1,0,0]
	ds_read_b128 v[96:99], v32 offset:6912
	ds_read_b128 v[88:91], v32 offset:6400
	ds_read_b128 v[104:107], v32 offset:7424
	ds_read_b128 v[92:95], v32 offset:6656
	s_waitcnt lgkmcnt(5)
	v_pk_mul_f32 v[156:157], v[54:55], v[80:81]
	v_pk_fma_f32 v[156:157], v[56:57], v[82:83], v[156:157]
	v_add_f32_e32 v2, v156, v157
	v_pk_mul_f32 v[8:9], v[54:55], v[132:133]
	v_pk_fma_f32 v[8:9], v[56:57], v[134:135], v[8:9]
	v_add_f32_dpp v2, v2, v2 row_ror:8 row_mask:0xf bank_mask:0xf bound_ctrl:1
	v_add_f32_e32 v12, v8, v9
	v_pk_mul_f32 v[4:5], v[76:77], v[152:153] op_sel_hi:[1,0]
	v_add_f32_dpp v2, v2, v2 row_ror:4 row_mask:0xf bank_mask:0xf bound_ctrl:1
	v_pk_mul_f32 v[6:7], v[78:79], v[152:153] op_sel_hi:[1,0]
	v_pk_fma_f32 v[4:5], v[54:55], v[68:69], v[4:5]
	v_add_f32_dpp v2, v2, v2 row_ror:2 row_mask:0xf bank_mask:0xf bound_ctrl:1
	v_pk_fma_f32 v[6:7], v[56:57], v[70:71], v[6:7]
	ds_read_b128 v[120:123], v32 offset:8448
	v_add_f32_dpp v2, v2, v2 row_ror:1 row_mask:0xf bank_mask:0xf bound_ctrl:1
	v_pk_fma_f32 v[54:55], v[84:85], v[2:3], v[4:5] op_sel_hi:[1,0,1] neg_lo:[1,0,0] neg_hi:[1,0,0]
	v_pk_fma_f32 v[56:57], v[86:87], v[2:3], v[6:7] op_sel_hi:[1,0,1] neg_lo:[1,0,0] neg_hi:[1,0,0]
	ds_read_b128 v[116:119], v32 offset:8192
	ds_read2_b32 v[154:155], v33 offset0:96 offset1:112
	ds_read_b128 v[108:111], v32 offset:7680
	ds_read_b128 v[124:127], v32 offset:8704
	ds_read_b128 v[112:115], v32 offset:7936
	s_waitcnt lgkmcnt(6)
	v_pk_mul_f32 v[156:157], v[54:55], v[100:101]
	v_pk_fma_f32 v[156:157], v[56:57], v[102:103], v[156:157]
	v_add_f32_e32 v2, v156, v157
	v_pk_mul_f32 v[8:9], v[54:55], v[72:73]
	v_pk_fma_f32 v[8:9], v[56:57], v[74:75], v[8:9]
	v_add_f32_dpp v2, v2, v2 row_ror:8 row_mask:0xf bank_mask:0xf bound_ctrl:1
	v_add_f32_e32 v13, v8, v9
	v_pk_mul_f32 v[4:5], v[96:97], v[152:153] op_sel:[0,1] op_sel_hi:[1,1]
	v_add_f32_dpp v2, v2, v2 row_ror:4 row_mask:0xf bank_mask:0xf bound_ctrl:1
	v_pk_mul_f32 v[6:7], v[98:99], v[152:153] op_sel:[0,1] op_sel_hi:[1,1]
	v_pk_fma_f32 v[4:5], v[54:55], v[88:89], v[4:5]
	v_add_f32_dpp v2, v2, v2 row_ror:2 row_mask:0xf bank_mask:0xf bound_ctrl:1
	v_pk_fma_f32 v[6:7], v[56:57], v[90:91], v[6:7]
	ds_read_b128 v[140:143], v32 offset:9728
	v_add_f32_dpp v2, v2, v2 row_ror:1 row_mask:0xf bank_mask:0xf bound_ctrl:1
	v_pk_fma_f32 v[54:55], v[104:105], v[2:3], v[4:5] op_sel_hi:[1,0,1] neg_lo:[1,0,0] neg_hi:[1,0,0]
	v_pk_fma_f32 v[56:57], v[106:107], v[2:3], v[6:7] op_sel_hi:[1,0,1] neg_lo:[1,0,0] neg_hi:[1,0,0]
	ds_read_b128 v[136:139], v32 offset:9472
	ds_read_b128 v[128:131], v32 offset:8960
	ds_read_b128 v[144:147], v32 offset:9984
	ds_read_b128 v[132:135], v32 offset:9216
	s_waitcnt lgkmcnt(5)
	v_pk_mul_f32 v[156:157], v[54:55], v[120:121]
	v_pk_fma_f32 v[156:157], v[56:57], v[122:123], v[156:157]
	v_add_f32_e32 v2, v156, v157
	v_pk_mul_f32 v[8:9], v[54:55], v[92:93]
	v_pk_fma_f32 v[8:9], v[56:57], v[94:95], v[8:9]
	v_add_f32_dpp v2, v2, v2 row_ror:8 row_mask:0xf bank_mask:0xf bound_ctrl:1
	v_add_f32_e32 v14, v8, v9
	v_pk_mul_f32 v[4:5], v[116:117], v[154:155] op_sel_hi:[1,0]
	v_add_f32_dpp v2, v2, v2 row_ror:4 row_mask:0xf bank_mask:0xf bound_ctrl:1
	v_pk_mul_f32 v[6:7], v[118:119], v[154:155] op_sel_hi:[1,0]
	v_pk_fma_f32 v[4:5], v[54:55], v[108:109], v[4:5]
	v_add_f32_dpp v2, v2, v2 row_ror:2 row_mask:0xf bank_mask:0xf bound_ctrl:1
	v_pk_fma_f32 v[6:7], v[56:57], v[110:111], v[6:7]
	ds_read_b128 v[80:83], v32 offset:11008
	v_add_f32_dpp v2, v2, v2 row_ror:1 row_mask:0xf bank_mask:0xf bound_ctrl:1
	v_pk_fma_f32 v[54:55], v[124:125], v[2:3], v[4:5] op_sel_hi:[1,0,1] neg_lo:[1,0,0] neg_hi:[1,0,0]
	v_pk_fma_f32 v[56:57], v[126:127], v[2:3], v[6:7] op_sel_hi:[1,0,1] neg_lo:[1,0,0] neg_hi:[1,0,0]
	ds_read_b128 v[76:79], v32 offset:10752
	ds_read2_b32 v[148:149], v33 offset0:128 offset1:144
	ds_read_b128 v[68:71], v32 offset:10240
	ds_read_b128 v[84:87], v32 offset:11264
	ds_read_b128 v[72:75], v32 offset:10496
	s_waitcnt lgkmcnt(6)
	v_pk_mul_f32 v[156:157], v[54:55], v[140:141]
	v_pk_fma_f32 v[156:157], v[56:57], v[142:143], v[156:157]
	v_add_f32_e32 v2, v156, v157
	v_pk_mul_f32 v[8:9], v[54:55], v[112:113]
	v_pk_fma_f32 v[8:9], v[56:57], v[114:115], v[8:9]
	v_add_f32_dpp v2, v2, v2 row_ror:8 row_mask:0xf bank_mask:0xf bound_ctrl:1
	v_add_f32_e32 v15, v8, v9
	v_pk_mul_f32 v[4:5], v[136:137], v[154:155] op_sel:[0,1] op_sel_hi:[1,1]
	v_add_f32_dpp v2, v2, v2 row_ror:4 row_mask:0xf bank_mask:0xf bound_ctrl:1
	v_pk_mul_f32 v[6:7], v[138:139], v[154:155] op_sel:[0,1] op_sel_hi:[1,1]
	v_pk_fma_f32 v[4:5], v[54:55], v[128:129], v[4:5]
	v_add_f32_dpp v2, v2, v2 row_ror:2 row_mask:0xf bank_mask:0xf bound_ctrl:1
	v_pk_fma_f32 v[6:7], v[56:57], v[130:131], v[6:7]
	ds_read_b128 v[100:103], v32 offset:12288
	v_add_f32_dpp v2, v2, v2 row_ror:1 row_mask:0xf bank_mask:0xf bound_ctrl:1
	v_pk_fma_f32 v[54:55], v[144:145], v[2:3], v[4:5] op_sel_hi:[1,0,1] neg_lo:[1,0,0] neg_hi:[1,0,0]
	v_pk_fma_f32 v[56:57], v[146:147], v[2:3], v[6:7] op_sel_hi:[1,0,1] neg_lo:[1,0,0] neg_hi:[1,0,0]
	ds_read_b128 v[96:99], v32 offset:12032
	ds_read_b128 v[88:91], v32 offset:11520
	ds_read_b128 v[104:107], v32 offset:12544
	ds_read_b128 v[92:95], v32 offset:11776
	s_waitcnt lgkmcnt(5)
	v_pk_mul_f32 v[156:157], v[54:55], v[80:81]
	v_pk_fma_f32 v[156:157], v[56:57], v[82:83], v[156:157]
	v_add_f32_e32 v2, v156, v157
	v_pk_mul_f32 v[8:9], v[54:55], v[132:133]
	v_pk_fma_f32 v[8:9], v[56:57], v[134:135], v[8:9]
	v_add_f32_dpp v2, v2, v2 row_ror:8 row_mask:0xf bank_mask:0xf bound_ctrl:1
	v_add_f32_e32 v16, v8, v9
	v_pk_mul_f32 v[4:5], v[76:77], v[148:149] op_sel_hi:[1,0]
	v_add_f32_dpp v2, v2, v2 row_ror:4 row_mask:0xf bank_mask:0xf bound_ctrl:1
	v_pk_mul_f32 v[6:7], v[78:79], v[148:149] op_sel_hi:[1,0]
	v_pk_fma_f32 v[4:5], v[54:55], v[68:69], v[4:5]
	v_add_f32_dpp v2, v2, v2 row_ror:2 row_mask:0xf bank_mask:0xf bound_ctrl:1
	v_pk_fma_f32 v[6:7], v[56:57], v[70:71], v[6:7]
	ds_read_b128 v[120:123], v32 offset:13568
	v_add_f32_dpp v2, v2, v2 row_ror:1 row_mask:0xf bank_mask:0xf bound_ctrl:1
	v_pk_fma_f32 v[54:55], v[84:85], v[2:3], v[4:5] op_sel_hi:[1,0,1] neg_lo:[1,0,0] neg_hi:[1,0,0]
	v_pk_fma_f32 v[56:57], v[86:87], v[2:3], v[6:7] op_sel_hi:[1,0,1] neg_lo:[1,0,0] neg_hi:[1,0,0]
	ds_read_b128 v[116:119], v32 offset:13312
	ds_read2_b32 v[150:151], v33 offset0:160 offset1:176
	ds_read_b128 v[108:111], v32 offset:12800
	ds_read_b128 v[124:127], v32 offset:13824
	ds_read_b128 v[112:115], v32 offset:13056
	s_waitcnt lgkmcnt(6)
	v_pk_mul_f32 v[156:157], v[54:55], v[100:101]
	v_pk_fma_f32 v[156:157], v[56:57], v[102:103], v[156:157]
	v_add_f32_e32 v2, v156, v157
	v_pk_mul_f32 v[8:9], v[54:55], v[72:73]
	v_pk_fma_f32 v[8:9], v[56:57], v[74:75], v[8:9]
	v_add_f32_dpp v2, v2, v2 row_ror:8 row_mask:0xf bank_mask:0xf bound_ctrl:1
	v_add_f32_e32 v17, v8, v9
	v_pk_mul_f32 v[4:5], v[96:97], v[148:149] op_sel:[0,1] op_sel_hi:[1,1]
	v_add_f32_dpp v2, v2, v2 row_ror:4 row_mask:0xf bank_mask:0xf bound_ctrl:1
	v_pk_mul_f32 v[6:7], v[98:99], v[148:149] op_sel:[0,1] op_sel_hi:[1,1]
	v_pk_fma_f32 v[4:5], v[54:55], v[88:89], v[4:5]
	v_add_f32_dpp v2, v2, v2 row_ror:2 row_mask:0xf bank_mask:0xf bound_ctrl:1
	v_pk_fma_f32 v[6:7], v[56:57], v[90:91], v[6:7]
	ds_read_b128 v[140:143], v32 offset:14848
	v_add_f32_dpp v2, v2, v2 row_ror:1 row_mask:0xf bank_mask:0xf bound_ctrl:1
	v_pk_fma_f32 v[54:55], v[104:105], v[2:3], v[4:5] op_sel_hi:[1,0,1] neg_lo:[1,0,0] neg_hi:[1,0,0]
	v_pk_fma_f32 v[56:57], v[106:107], v[2:3], v[6:7] op_sel_hi:[1,0,1] neg_lo:[1,0,0] neg_hi:[1,0,0]
	ds_read_b128 v[136:139], v32 offset:14592
	ds_read_b128 v[128:131], v32 offset:14080
	ds_read_b128 v[144:147], v32 offset:15104
	ds_read_b128 v[132:135], v32 offset:14336
	s_waitcnt lgkmcnt(5)
	v_pk_mul_f32 v[156:157], v[54:55], v[120:121]
	v_pk_fma_f32 v[156:157], v[56:57], v[122:123], v[156:157]
	v_add_f32_e32 v2, v156, v157
	v_pk_mul_f32 v[8:9], v[54:55], v[92:93]
	v_pk_fma_f32 v[8:9], v[56:57], v[94:95], v[8:9]
	v_add_f32_dpp v2, v2, v2 row_ror:8 row_mask:0xf bank_mask:0xf bound_ctrl:1
	v_add_f32_e32 v18, v8, v9
	v_pk_mul_f32 v[4:5], v[116:117], v[150:151] op_sel_hi:[1,0]
	v_add_f32_dpp v2, v2, v2 row_ror:4 row_mask:0xf bank_mask:0xf bound_ctrl:1
	v_pk_mul_f32 v[6:7], v[118:119], v[150:151] op_sel_hi:[1,0]
	v_pk_fma_f32 v[4:5], v[54:55], v[108:109], v[4:5]
	v_add_f32_dpp v2, v2, v2 row_ror:2 row_mask:0xf bank_mask:0xf bound_ctrl:1
	v_pk_fma_f32 v[6:7], v[56:57], v[110:111], v[6:7]
	ds_read_b128 v[80:83], v32 offset:16128
	v_add_f32_dpp v2, v2, v2 row_ror:1 row_mask:0xf bank_mask:0xf bound_ctrl:1
	v_pk_fma_f32 v[54:55], v[124:125], v[2:3], v[4:5] op_sel_hi:[1,0,1] neg_lo:[1,0,0] neg_hi:[1,0,0]
	v_pk_fma_f32 v[56:57], v[126:127], v[2:3], v[6:7] op_sel_hi:[1,0,1] neg_lo:[1,0,0] neg_hi:[1,0,0]
	ds_read_b128 v[76:79], v32 offset:15872
	ds_read2_b32 v[152:153], v33 offset0:192 offset1:208
	ds_read_b128 v[68:71], v32 offset:15360
	ds_read_b128 v[84:87], v32 offset:16384
	ds_read_b128 v[72:75], v32 offset:15616
	s_waitcnt lgkmcnt(6)
	v_pk_mul_f32 v[156:157], v[54:55], v[140:141]
	v_pk_fma_f32 v[156:157], v[56:57], v[142:143], v[156:157]
	v_add_f32_e32 v2, v156, v157
	v_pk_mul_f32 v[8:9], v[54:55], v[112:113]
	v_pk_fma_f32 v[8:9], v[56:57], v[114:115], v[8:9]
	v_add_f32_dpp v2, v2, v2 row_ror:8 row_mask:0xf bank_mask:0xf bound_ctrl:1
	v_add_f32_e32 v19, v8, v9
	v_pk_mul_f32 v[4:5], v[136:137], v[150:151] op_sel:[0,1] op_sel_hi:[1,1]
	v_add_f32_dpp v2, v2, v2 row_ror:4 row_mask:0xf bank_mask:0xf bound_ctrl:1
	v_pk_mul_f32 v[6:7], v[138:139], v[150:151] op_sel:[0,1] op_sel_hi:[1,1]
	v_pk_fma_f32 v[4:5], v[54:55], v[128:129], v[4:5]
	v_add_f32_dpp v2, v2, v2 row_ror:2 row_mask:0xf bank_mask:0xf bound_ctrl:1
	v_pk_fma_f32 v[6:7], v[56:57], v[130:131], v[6:7]
	ds_read_b128 v[100:103], v32 offset:17408
	v_add_f32_dpp v2, v2, v2 row_ror:1 row_mask:0xf bank_mask:0xf bound_ctrl:1
	v_pk_fma_f32 v[54:55], v[144:145], v[2:3], v[4:5] op_sel_hi:[1,0,1] neg_lo:[1,0,0] neg_hi:[1,0,0]
	v_pk_fma_f32 v[56:57], v[146:147], v[2:3], v[6:7] op_sel_hi:[1,0,1] neg_lo:[1,0,0] neg_hi:[1,0,0]
	ds_read_b128 v[96:99], v32 offset:17152
	ds_read_b128 v[88:91], v32 offset:16640
	ds_read_b128 v[104:107], v32 offset:17664
	ds_read_b128 v[92:95], v32 offset:16896
	s_waitcnt lgkmcnt(5)
	v_pk_mul_f32 v[156:157], v[54:55], v[80:81]
	v_pk_fma_f32 v[156:157], v[56:57], v[82:83], v[156:157]
	v_add_f32_e32 v2, v156, v157
	v_pk_mul_f32 v[8:9], v[54:55], v[132:133]
	v_pk_fma_f32 v[8:9], v[56:57], v[134:135], v[8:9]
	v_add_f32_dpp v2, v2, v2 row_ror:8 row_mask:0xf bank_mask:0xf bound_ctrl:1
	v_add_f32_e32 v20, v8, v9
	v_pk_mul_f32 v[4:5], v[76:77], v[152:153] op_sel_hi:[1,0]
	v_add_f32_dpp v2, v2, v2 row_ror:4 row_mask:0xf bank_mask:0xf bound_ctrl:1
	v_pk_mul_f32 v[6:7], v[78:79], v[152:153] op_sel_hi:[1,0]
	v_pk_fma_f32 v[4:5], v[54:55], v[68:69], v[4:5]
	v_add_f32_dpp v2, v2, v2 row_ror:2 row_mask:0xf bank_mask:0xf bound_ctrl:1
	v_pk_fma_f32 v[6:7], v[56:57], v[70:71], v[6:7]
	ds_read_b128 v[120:123], v32 offset:18688
	v_add_f32_dpp v2, v2, v2 row_ror:1 row_mask:0xf bank_mask:0xf bound_ctrl:1
	v_pk_fma_f32 v[54:55], v[84:85], v[2:3], v[4:5] op_sel_hi:[1,0,1] neg_lo:[1,0,0] neg_hi:[1,0,0]
	v_pk_fma_f32 v[56:57], v[86:87], v[2:3], v[6:7] op_sel_hi:[1,0,1] neg_lo:[1,0,0] neg_hi:[1,0,0]
	ds_read_b128 v[116:119], v32 offset:18432
	ds_read2_b32 v[154:155], v33 offset0:224 offset1:240
	ds_read_b128 v[108:111], v32 offset:17920
	ds_read_b128 v[124:127], v32 offset:18944
	ds_read_b128 v[112:115], v32 offset:18176
	s_waitcnt lgkmcnt(6)
	v_pk_mul_f32 v[156:157], v[54:55], v[100:101]
	v_pk_fma_f32 v[156:157], v[56:57], v[102:103], v[156:157]
	v_add_f32_e32 v2, v156, v157
	v_pk_mul_f32 v[8:9], v[54:55], v[72:73]
	v_pk_fma_f32 v[8:9], v[56:57], v[74:75], v[8:9]
	v_add_f32_dpp v2, v2, v2 row_ror:8 row_mask:0xf bank_mask:0xf bound_ctrl:1
	v_add_f32_e32 v21, v8, v9
	v_pk_mul_f32 v[4:5], v[96:97], v[152:153] op_sel:[0,1] op_sel_hi:[1,1]
	v_add_f32_dpp v2, v2, v2 row_ror:4 row_mask:0xf bank_mask:0xf bound_ctrl:1
	v_pk_mul_f32 v[6:7], v[98:99], v[152:153] op_sel:[0,1] op_sel_hi:[1,1]
	v_pk_fma_f32 v[4:5], v[54:55], v[88:89], v[4:5]
	v_add_f32_dpp v2, v2, v2 row_ror:2 row_mask:0xf bank_mask:0xf bound_ctrl:1
	v_pk_fma_f32 v[6:7], v[56:57], v[90:91], v[6:7]
	ds_read_b128 v[140:143], v32 offset:19968
	v_add_f32_dpp v2, v2, v2 row_ror:1 row_mask:0xf bank_mask:0xf bound_ctrl:1
	v_pk_fma_f32 v[54:55], v[104:105], v[2:3], v[4:5] op_sel_hi:[1,0,1] neg_lo:[1,0,0] neg_hi:[1,0,0]
	v_pk_fma_f32 v[56:57], v[106:107], v[2:3], v[6:7] op_sel_hi:[1,0,1] neg_lo:[1,0,0] neg_hi:[1,0,0]
	ds_read_b128 v[136:139], v32 offset:19712
	ds_read_b128 v[128:131], v32 offset:19200
	ds_read_b128 v[144:147], v32 offset:20224
	ds_read_b128 v[132:135], v32 offset:19456
	s_waitcnt lgkmcnt(5)
	s_add_i32 s13, s36, s83
	s_add_i32 s13, s13, 1
	s_and_b32 s13, s13, 3
	s_lshl_b32 s12, s13, 2
	s_add_i32 s12, s12, 0x15000
	s_mul_i32 s13, s13, 0x5400
	v_mov_b32_e32 v26, s12
	v_add_u32_e32 v34, s13, v183
	v_add_u32_e32 v35, s13, v184
	v_add_u32_e32 v35, 0x5000, v35
	v_pk_mul_f32 v[156:157], v[54:55], v[120:121]
	v_pk_fma_f32 v[156:157], v[56:57], v[122:123], v[156:157]
	v_add_f32_e32 v2, v156, v157
	v_pk_mul_f32 v[8:9], v[54:55], v[92:93]
	v_pk_fma_f32 v[8:9], v[56:57], v[94:95], v[8:9]
	v_add_f32_dpp v2, v2, v2 row_ror:8 row_mask:0xf bank_mask:0xf bound_ctrl:1
	v_add_f32_e32 v22, v8, v9
	v_pk_mul_f32 v[4:5], v[116:117], v[154:155] op_sel_hi:[1,0]
	v_add_f32_dpp v2, v2, v2 row_ror:4 row_mask:0xf bank_mask:0xf bound_ctrl:1
	v_pk_mul_f32 v[6:7], v[118:119], v[154:155] op_sel_hi:[1,0]
	v_pk_fma_f32 v[4:5], v[54:55], v[108:109], v[4:5]
	v_add_f32_dpp v2, v2, v2 row_ror:2 row_mask:0xf bank_mask:0xf bound_ctrl:1
	v_pk_fma_f32 v[6:7], v[56:57], v[110:111], v[6:7]
	ds_read_b32 v25, v26
	v_add_f32_dpp v2, v2, v2 row_ror:1 row_mask:0xf bank_mask:0xf bound_ctrl:1
	v_pk_fma_f32 v[54:55], v[124:125], v[2:3], v[4:5] op_sel_hi:[1,0,1] neg_lo:[1,0,0] neg_hi:[1,0,0]
	v_pk_fma_f32 v[56:57], v[126:127], v[2:3], v[6:7] op_sel_hi:[1,0,1] neg_lo:[1,0,0] neg_hi:[1,0,0]
	ds_read_b128 v[80:83], v34 offset:768
	ds_read_b128 v[76:79], v34 offset:512
	ds_read2_b32 v[148:149], v35 offset0:0 offset1:16
	ds_read_b128 v[68:71], v34 offset:0
	ds_read_b128 v[84:87], v34 offset:1024
	ds_read_b128 v[72:75], v34 offset:256
	s_waitcnt lgkmcnt(7)
	v_pk_mul_f32 v[156:157], v[54:55], v[140:141]
	v_pk_fma_f32 v[156:157], v[56:57], v[142:143], v[156:157]
	v_add_f32_e32 v2, v156, v157
	v_pk_mul_f32 v[8:9], v[54:55], v[112:113]
	v_pk_fma_f32 v[8:9], v[56:57], v[114:115], v[8:9]
	v_add_f32_dpp v2, v2, v2 row_ror:8 row_mask:0xf bank_mask:0xf bound_ctrl:1
	v_add_f32_e32 v23, v8, v9
	v_pk_mul_f32 v[4:5], v[136:137], v[154:155] op_sel:[0,1] op_sel_hi:[1,1]
	v_add_f32_dpp v2, v2, v2 row_ror:4 row_mask:0xf bank_mask:0xf bound_ctrl:1
	v_pk_mul_f32 v[6:7], v[138:139], v[154:155] op_sel:[0,1] op_sel_hi:[1,1]
	v_pk_fma_f32 v[4:5], v[54:55], v[128:129], v[4:5]
	v_add_f32_dpp v2, v2, v2 row_ror:2 row_mask:0xf bank_mask:0xf bound_ctrl:1
	v_pk_fma_f32 v[6:7], v[56:57], v[130:131], v[6:7]
	ds_read_b128 v[100:103], v34 offset:2048
	v_add_f32_dpp v2, v2, v2 row_ror:1 row_mask:0xf bank_mask:0xf bound_ctrl:1
	v_pk_fma_f32 v[54:55], v[144:145], v[2:3], v[4:5] op_sel_hi:[1,0,1] neg_lo:[1,0,0] neg_hi:[1,0,0]
	v_pk_fma_f32 v[56:57], v[146:147], v[2:3], v[6:7] op_sel_hi:[1,0,1] neg_lo:[1,0,0] neg_hi:[1,0,0]
	ds_read_b128 v[96:99], v34 offset:1792
	ds_read_b128 v[88:91], v34 offset:1280
	ds_read_b128 v[104:107], v34 offset:2304
	ds_read_b128 v[92:95], v34 offset:1536
	v_pk_mul_f32 v[8:9], v[54:55], v[132:133]
	v_pk_fma_f32 v[8:9], v[56:57], v[134:135], v[8:9]
	v_add_f32_e32 v24, v8, v9
	v_add_f32_dpp v66, v66, v66 row_ror:8 row_mask:0xf bank_mask:0x3
	v_add_f32_dpp v66, v17, v17 row_ror:8 row_mask:0xf bank_mask:0xc
	v_add_f32_dpp v10, v10, v10 row_ror:8 row_mask:0xf bank_mask:0x3
	v_add_f32_dpp v10, v18, v18 row_ror:8 row_mask:0xf bank_mask:0xc
	v_add_f32_dpp v11, v11, v11 row_ror:8 row_mask:0xf bank_mask:0x3
	v_add_f32_dpp v11, v19, v19 row_ror:8 row_mask:0xf bank_mask:0xc
	v_add_f32_dpp v12, v12, v12 row_ror:8 row_mask:0xf bank_mask:0x3
	v_add_f32_dpp v12, v20, v20 row_ror:8 row_mask:0xf bank_mask:0xc
	v_add_f32_dpp v13, v13, v13 row_ror:8 row_mask:0xf bank_mask:0x3
	v_add_f32_dpp v13, v21, v21 row_ror:8 row_mask:0xf bank_mask:0xc
	v_add_f32_dpp v14, v14, v14 row_ror:8 row_mask:0xf bank_mask:0x3
	v_add_f32_dpp v14, v22, v22 row_ror:8 row_mask:0xf bank_mask:0xc
	v_add_f32_dpp v15, v15, v15 row_ror:8 row_mask:0xf bank_mask:0x3
	v_add_f32_dpp v15, v23, v23 row_ror:8 row_mask:0xf bank_mask:0xc
	v_add_f32_dpp v16, v16, v16 row_ror:8 row_mask:0xf bank_mask:0x3
	v_add_f32_dpp v16, v24, v24 row_ror:8 row_mask:0xf bank_mask:0xc
	v_add_f32_dpp v66, v66, v66 row_shl:4 row_mask:0xf bank_mask:0x5
	v_add_f32_dpp v66, v13, v13 row_shr:4 row_mask:0xf bank_mask:0xa
	v_add_f32_dpp v10, v10, v10 row_shl:4 row_mask:0xf bank_mask:0x5
	v_add_f32_dpp v10, v14, v14 row_shr:4 row_mask:0xf bank_mask:0xa
	v_add_f32_dpp v11, v11, v11 row_shl:4 row_mask:0xf bank_mask:0x5
	v_add_f32_dpp v11, v15, v15 row_shr:4 row_mask:0xf bank_mask:0xa
	v_add_f32_dpp v12, v12, v12 row_shl:4 row_mask:0xf bank_mask:0x5
	v_add_f32_dpp v12, v16, v16 row_shr:4 row_mask:0xf bank_mask:0xa
	v_add_f32_dpp v27, v66, v66 quad_perm:[2,3,0,1] row_mask:0xf bank_mask:0xf
	v_add_f32_dpp v28, v11, v11 quad_perm:[2,3,0,1] row_mask:0xf bank_mask:0xf
	v_cndmask_b32_e64 v66, v27, v28, s[78:79]
	v_add_f32_dpp v27, v10, v10 quad_perm:[2,3,0,1] row_mask:0xf bank_mask:0xf
	v_add_f32_dpp v28, v12, v12 quad_perm:[2,3,0,1] row_mask:0xf bank_mask:0xf
	v_cndmask_b32_e64 v10, v27, v28, s[78:79]
	s_add_i32 s13, s86, 0x15010
	v_mov_b32_e32 v26, s13
	s_mov_b64 s[12:13], exec
	s_mov_b64 exec, s[38:39]
	ds_add_u32 v26, v203
	s_mov_b64 exec, s[12:13]
	v_add_f32_dpp v27, v10, v10 quad_perm:[1,0,3,2] row_mask:0xf bank_mask:0xf
	v_add_f32_dpp v28, v66, v66 quad_perm:[1,0,3,2] row_mask:0xf bank_mask:0xf
	v_cndmask_b32_e64 v66, v28, v27, s[96:97]
	v_lshl_add_u32 v64, s36, 4, v59
	v_ashrrev_i32_e32 v65, 31, v64
	v_lshlrev_b64 v[64:65], 12, v[64:65]
	s_add_i32 s36, s36, 1
	v_lshl_add_u64 v[64:65], v[62:63], 0, v[64:65]
	s_cmp_eq_u32 s36, s85
	global_store_dword v[64:65], v66, off
	s_cbranch_scc1 .Lsc_exit
	s_add_i32 s77, s36, s83
	s_and_b32 s86, s77, 3
	s_lshl_b32 s86, s86, 2
	s_add_i32 s77, s77, 1
	v_mov_b32_e32 v32, v34
	v_mov_b32_e32 v33, v35
	s_waitcnt lgkmcnt(12)
	v_cmp_le_u32_e32 vcc, s77, v25
	s_cbranch_vccnz .Lsc_chunk
	s_branch .Lsc_pollentry
.Lsc_exit:
	s_waitcnt lgkmcnt(0)
.LBB0_477:
	v_lshl_add_u64 v[60:61], v[60:61], 2, s[0:1]
	v_mov_b32_e32 v59, v1
	v_lshl_add_u64 v[58:59], v[60:61], 0, v[58:59]
	s_mov_b64 s[12:13], 0
	global_store_dwordx4 v[58:59], v[54:57], off

.LBB0_949:
	s_or_b64 exec, exec, s[38:39]
	s_mov_b64 s[12:13], exec
	v_mbcnt_lo_u32_b32 v0, s12, 0
	v_mbcnt_hi_u32_b32 v0, s13, v0
	v_cmp_eq_u32_e32 vcc, 0, v0
	s_and_saveexec_b64 s[38:39], vcc
	s_cbranch_execz .Lbar_e1
	s_bcnt1_i32_b64 s12, s[12:13]
	v_mov_b32_e32 v0, s12
	v_readlane_b32 s12, v252, 45
	v_readlane_b32 s13, v252, 46
	s_nop 4
	global_atomic_add v1, v0, s[12:13]
.Lbar_e1:
	s_or_b64 exec, exec, s[38:39]
	s_waitcnt vmcnt(0)
	buffer_inv sc1
	s_branch .Ltr_7
